# as v45 plus strategy 4 (one static priority raise) applied to the windowed-GQA attention tile loop: waves 0-3 (S-softmax-PV half) at s_setprio 1 for the whole unit, reset at loop exit
# speedup vs baseline: 1.0087x; 1.0025x over previous
; #define ATT_DMA(t, sk, sv) do { glds16(ksrc + (long)(t) * 64 * a.ldk, (unsigned)__builtin_amdgcn_readfirstlane(kdst + (sk) * KSLOT)); \
;         if (MODE == 0 && wid < 4) glds16(kpsrc + (long)(t) * 64 * 32, (unsigned)__builtin_amdgcn_readfirstlane(kpdst + (sk) * KSLOT)); \
;         glds16(vsrc + (long)(t) * 64 * a.ldv, (unsigned)__builtin_amdgcn_readfirstlane(vdst + (sv) * VSLOT)); } while (0)
; template <int MODE> __device__ __forceinline__ void attn_unit(const Unit& a, char* shm) {
;     ...
;     const bf16_t* ksrc = a.K + (long)lane * a.ldk + wid * 8;
;     const bf16_t* kpsrc = a.KPE + (long)lane * 32 + (wid & 3) * 8;
;     const bf16_t* vsrc = a.V + (long)(16 * (wid & 3) + (lane >> 2)) * a.ldv + (wid >> 2) * 32 + (lane & 3) * 8;
;     const unsigned kdst = lds0 + LDS_K + wid * 1024, kpdst = lds0 + LDS_K + (8 + (wid & 3)) * 1024, vdst = lds0 + LDS_V + wid * 1024;
;     ...
;     const int g = wid >> 2;
;     ATT_DMA(a.t_lo, 0, 0);
; __global__ void __launch_bounds__(NTHREADS) mk_fwd(Params P) {
;     ...
;                     for (int u = vcu; u < 1024; u += G) { const int rb = u >> 3, h = u & 7; const size_t r0 = (size_t)rb * 256;
;                         const int S = r0 < TP ? 8192 : 4096; const int qpos0 = (int)(r0 & (size_t)(S - 1)); const size_t seq0 = r0 - qpos0;
;                         att::Unit a; a.Q = Z2 + r0 * ZLD + 512 + h * 64; a.ldq = ZLD; a.K = Z2 + seq0 * ZLD + 1536 + (h >> 2) * 64; a.ldk = ZLD; a.KPE = nullptr;
;                         a.V = Z2 + seq0 * ZLD + 1664 + (h >> 2) * 64; a.ldv = ZLD; a.O = Z2 + r0 * ZLD + 512 + h * 64; a.ldo = ZLD;
;                         a.t_lo = max(0, qpos0 / 64 - 2); a.t_hi = min(S / 64, qpos0 / 64 + 6); a.qpos0 = qpos0;
;                         a.slope2 = exp2f(-(float)(h + 1)) * LOG2E; a.sink2 = P.in[I_SINK][jj * 8 + h] * LOG2E;
.LBB0_1322:
	s_ashr_i32 s0, s22, 3
	s_ashr_i32 s1, s0, 31
	s_lshl_b64 s[2:3], s[0:1], 8
	v_mov_b64_e32 v[0:1], 0x4000
	s_and_b32 s12, s22, 7
	v_cmp_lt_u64_e32 vcc, s[2:3], v[0:1]
	s_and_b64 s[24:25], vcc, exec
	s_movk_i32 s1, 0x1000
	s_cselect_b32 s15, 0x2000, s1
	s_add_i32 s1, s15, -1
	s_and_b32 s1, s1, s2
	s_sub_u32 s16, s2, s1
	s_subb_u32 s18, s3, 0
	s_mul_hi_i32 s2, s0, 0x160000
	s_mul_i32 s0, s0, 0x160000
	s_add_u32 s0, s36, s0
	s_addc_u32 s3, s37, s2
	s_lshl_b32 s2, s12, 7
	s_add_u32 s2, s0, s2
	s_mulk_i32 s18, 0x1600
	s_mul_hi_u32 s0, s16, 0x1600
	s_addc_u32 s3, s3, 0
	s_add_i32 s0, s0, s18
	s_mulk_i32 s16, 0x1600
	s_add_u32 s16, s36, s16
	s_addc_u32 s0, s37, s0
	s_lshl_b32 s18, s22, 5
	s_and_b32 s18, s18, 0x80
	s_add_u32 s28, s16, s18
	s_addc_u32 s29, s0, 0
	s_lshr_b32 s16, s1, 6
	s_lshr_b32 s0, s15, 6
	s_add_i32 s15, s16, 6
	s_min_u32 s26, s0, s15
	v_readlane_b32 s0, v255, 28
	s_or_b32 s58, s12, s0
	s_lshl_b64 s[24:25], s[58:59], 2
	v_readlane_b32 s30, v254, 47
	v_readlane_b32 s31, v254, 48
	s_add_u32 s24, s30, s24
	s_addc_u32 s25, s31, s25
	global_load_dword v4, v81, s[24:25]
	v_mov_b32_e32 v8, v167
	v_sub_u32_e64 v5, s16, 2 clamp
	v_readfirstlane_b32 s15, v8
	s_ashr_i32 s24, s15, 6
	v_and_b32_e32 v158, 63, v8
	s_lshl_b32 s0, s24, 4
	v_bfe_u32 v2, v8, 2, 4
	v_mul_u32_u24_e32 v0, 0xb00, v158
	v_and_or_b32 v2, s0, 48, v2
	v_lshlrev_b32_e32 v80, 1, v0
	v_mul_u32_u24_e32 v2, 0xb00, v2
	v_lshl_add_u64 v[0:1], s[28:29], 0, v[80:81]
	v_lshlrev_b32_e32 v80, 1, v2
	s_ashr_i32 s0, s15, 3
	s_lshl_b32 s30, s24, 3
	v_lshl_add_u64 v[2:3], s[28:29], 0, v[80:81]
	s_and_b32 s28, s0, 0xffffffe0
	v_lshlrev_b32_e32 v159, 3, v8
	s_ashr_i32 s31, s30, 31
	s_ashr_i32 s29, s28, 31
	v_and_b32_e32 v9, 24, v159
	s_and_b32 s18, s15, 0x3fffffc0
	v_lshl_add_u64 v[0:1], s[30:31], 1, v[0:1]
	s_mov_b64 s[30:31], 0xc00
	v_lshl_add_u64 v[2:3], s[28:29], 1, v[2:3]
	v_lshlrev_b32_e32 v80, 1, v9
	s_lshl_b32 s27, s24, 10
	v_lshl_add_u64 v[0:1], v[0:1], 0, s[30:31]
	v_lshl_add_u64 v[2:3], v[2:3], 0, v[80:81]
	s_mov_b64 s[28:29], 0xd00
	s_cmp_lg_u32 0, -1
	s_mov_b32 s23, 0x58000
	v_lshl_add_u64 v[2:3], v[2:3], 0, s[28:29]
	s_cselect_b32 s21, 0, 0
	v_mad_u64_u32 v[6:7], s[30:31], v5, s23, v[0:1]
	s_add_i32 s27, s27, s21
	s_mov_b32 s21, m0
	s_mov_b32 m0, s27
	s_nop 0
	global_load_lds_dwordx4 v[6:7], off
	s_mov_b32 m0, s21
	v_mad_u64_u32 v[6:7], s[30:31], v5, s23, v[2:3]
	s_add_i32 s28, s27, 0x6000
	s_mov_b32 s21, m0
	s_mov_b32 m0, s28
	s_nop 0
	global_load_lds_dwordx4 v[6:7], off
	s_mov_b32 m0, s21
	v_lshlrev_b32_e32 v6, 1, v8
	v_and_b32_e32 v160, 31, v8
	v_bfe_u32 v161, v8, 5, 1
	s_lshl_b32 s18, s18, 2
	v_and_b32_e32 v6, 32, v6
	v_lshlrev_b32_e32 v8, 4, v8
	s_add_i32 s25, s18, 0
	v_cmp_gt_u32_e64 s[42:43], 32, v158
	v_add3_u32 v6, 0, v6, v9
	v_lshlrev_b32_e32 v7, 8, v161
	v_and_b32_e32 v8, 0xc0, v8
	v_cmp_le_u32_e32 vcc, s26, v5
	s_mov_b32 s0, 0
	s_lshl_b32 s23, s24, 5
	v_mov_b32_e32 v15, 0
	v_cndmask_b32_e64 v162, 0, 1.0, s[42:43]
	v_add3_u32 v164, v6, v7, v8
	s_mov_b32 s29, 0
	v_lshl_add_u32 v163, v160, 2, s25
	s_cbranch_vccnz .LBB0_1339
; #define ATT_DMA(t, sk, sv) do { glds16(ksrc + (long)(t) * 64 * a.ldk, (unsigned)__builtin_amdgcn_readfirstlane(kdst + (sk) * KSLOT)); \
;         if (MODE == 0 && wid < 4) glds16(kpsrc + (long)(t) * 64 * 32, (unsigned)__builtin_amdgcn_readfirstlane(kpdst + (sk) * KSLOT)); \
;         glds16(vsrc + (long)(t) * 64 * a.ldv, (unsigned)__builtin_amdgcn_readfirstlane(vdst + (sv) * VSLOT)); } while (0)
; #define ATT_WAIT_BAR() asm volatile("s_waitcnt vmcnt(0) lgkmcnt(0)\n\ts_barrier" ::: "memory")
; template <int MODE> __device__ __forceinline__ void attn_unit(const Unit& a, char* shm) {
;     ...
;     { const bf16_t* Qw = a.Q + (long)(wid * 32 + r32) * a.ldq + hi * 8;
; #pragma unroll
;       for (int d0 = 0; d0 < ND; ++d0) qr[d0] = *(const bf16x8*)(Qw + d0 * 16); }
;     float mhat = (MODE == 1) ? a.sink2 : 0.f;
;     float l_reg = (MODE == 1 && hi == 0) ? 1.f : 0.f;
;     f32x16 o[2]; o[0] = f32x16{}; o[1] = f32x16{};
;     f32x16 negm;
; #pragma unroll
;     for (int r = 0; r < 16; ++r) negm[r] = -mhat;
;     const int tq0 = a.qpos0 + wid * 32, tq = tq0 + r32;
;     const lds_cptr vp0 = shm3 + LDS_V + ((lane >> 4) & 1) * 32 + (lane & 3) * 8 + (4 * hi + ((lane & 15) >> 2)) * 64;
;     u32x4 pw[4]; pw[0] = (u32x4){0u, 0u, 0u, 0u}; pw[1] = pw[0]; pw[2] = pw[0]; pw[3] = pw[0];
;     bool pend = false; int sv = 0, svp = 0;
;     for (int t = a.t_lo; t < a.t_hi; ++t) {
;         const int s = (t - a.t_lo) & 1;
;         ATT_WAIT_BAR();
;         if (t + 1 < a.t_hi) ATT_DMA(t + 1, s ^ 1, (sv == 2 ? 0 : sv + 1));
	v_or_b32_e32 v5, s23, v160
	v_mov_b64_e32 v[6:7], s[2:3]
	v_mad_i64_i32 v[6:7], s[34:35], v5, s11, v[6:7]
	v_lshlrev_b32_e32 v80, 4, v161
	v_lshl_add_u64 v[6:7], v[6:7], 0, v[80:81]
	global_load_dwordx4 v[82:85], v[6:7], off offset:1024
	global_load_dwordx4 v[86:89], v[6:7], off offset:1056
	global_load_dwordx4 v[90:93], v[6:7], off offset:1088
	global_load_dwordx4 v[94:97], v[6:7], off offset:1120
	s_add_i32 s12, s12, 1
	v_cvt_f32_ubyte0_e32 v5, s12
	s_mov_b32 s0, 0x42fc0000
	v_cmp_lt_f32_e32 vcc, s0, v5
	v_mov_b32_e32 v6, 0x42800000
	s_max_u32 s30, s16, 2
	v_cndmask_b32_e32 v6, 0, v6, vcc
	v_sub_f32_e32 v5, v6, v5
	v_exp_f32_e32 v5, v5
	s_and_b64 s[34:35], vcc, exec
	s_cselect_b32 s0, 0xffffffc0, 0
	s_waitcnt vmcnt(0)
	v_mul_f32_e32 v165, 0x3fb8aa3b, v4
	v_ldexp_f32 v5, v5, s0
	v_mul_f32_e32 v98, 0x3fb8aa3b, v5
	v_lshlrev_b32_e32 v4, 10, v161
	v_lshlrev_b32_e32 v5, 4, v160
	v_add3_u32 v166, 0, v4, v5
	v_not_b32_e32 v4, 16
	v_mad_i32_i24 v109, v161, -4, v4
	v_not_b32_e32 v4, 18
	v_mad_i32_i24 v111, v161, -4, v4
	v_not_b32_e32 v4, 17
	v_mad_i32_i24 v110, v161, -4, v4
	v_not_b32_e32 v4, 24
	v_mad_i32_i24 v113, v161, -4, v4
	v_not_b32_e32 v4, 23
	v_mad_i32_i24 v112, v161, -4, v4
	v_not_b32_e32 v4, 26
	v_mad_i32_i24 v115, v161, -4, v4
	v_not_b32_e32 v4, 25
	v_mad_i32_i24 v114, v161, -4, v4
	v_not_b32_e32 v4, 32
	v_mad_i32_i24 v117, v161, -4, v4
	v_not_b32_e32 v4, 31
	v_mad_i32_i24 v116, v161, -4, v4
	v_not_b32_e32 v4, 34
	v_mad_i32_i24 v119, v161, -4, v4
	v_not_b32_e32 v4, 33
	v_mad_i32_i24 v118, v161, -4, v4
	v_not_b32_e32 v4, 40
	v_mad_i32_i24 v121, v161, -4, v4
	v_not_b32_e32 v4, 39
	v_mad_i32_i24 v120, v161, -4, v4
	v_not_b32_e32 v4, 42
	v_mad_i32_i24 v123, v161, -4, v4
	v_not_b32_e32 v4, 41
	v_mad_i32_i24 v122, v161, -4, v4
	v_not_b32_e32 v4, 48
	v_mad_i32_i24 v125, v161, -4, v4
	v_not_b32_e32 v4, 47
	v_mad_i32_i24 v124, v161, -4, v4
	v_not_b32_e32 v4, 50
	v_mad_i32_i24 v127, v161, -4, v4
	v_not_b32_e32 v4, 49
	s_add_i32 s0, s23, s1
	v_mad_i32_i24 v126, v161, -4, v4
	v_not_b32_e32 v4, 56
	s_add_i32 s31, s0, 0xffffff80
	s_add_i32 s40, s0, 0x9f
	v_mad_i32_i24 v129, v161, -4, v4
	v_not_b32_e32 v4, 55
	s_cmpk_lt_u32 s15, 0x100
	v_mad_i32_i24 v128, v161, -4, v4
	v_not_b32_e32 v4, 58
	s_cselect_b64 s[44:45], -1, 0
	v_mad_i32_i24 v137, v161, -4, v4
	v_not_b32_e32 v4, 57
	s_addk_i32 s0, 0x80
	v_mad_i32_i24 v136, v161, -4, v4
	v_add_u32_e32 v4, s0, v160
	s_lshl_b32 s0, s30, 6
	v_subrev_u32_e32 v168, s0, v4
	s_add_i32 s12, s30, -1
	v_mov_b32_e32 v4, 0x58000
	v_mov_b32_e32 v48, 0
	v_xor_b32_e32 v32, 0x80000000, v165
	s_add_i32 s41, s0, 0xffffff80
	v_mad_u64_u32 v[138:139], s[0:1], s12, v4, v[0:1]
	v_mad_u64_u32 v[140:141], s[0:1], s12, v4, v[2:3]
	v_mul_i32_i24_e32 v100, -4, v161
	v_mad_i32_i24 v101, v161, -4, -1
	v_mad_i32_i24 v103, v161, -4, -3
	v_mad_i32_i24 v102, v161, -4, -2
	v_mad_i32_i24 v105, v161, -4, -9
	v_mad_i32_i24 v104, v161, -4, -8
	v_mad_i32_i24 v107, v161, -4, -11
	v_mad_i32_i24 v106, v161, -4, -10
	v_mad_i32_i24 v108, v161, -4, -16
	v_mov_b32_e32 v99, v98
	s_mov_b64 s[46:47], 0
	s_mov_b32 s0, 0
	s_mov_b32 s12, 0
	v_mov_b32_e32 v49, v48
	v_mov_b32_e32 v50, v48
	v_mov_b32_e32 v51, v48
	v_mov_b32_e32 v60, v48
	v_mov_b32_e32 v61, v48
	v_mov_b32_e32 v62, v48
	v_mov_b32_e32 v63, v48
	v_mov_b32_e32 v56, v48
	v_mov_b32_e32 v57, v48
	v_mov_b32_e32 v58, v48
	v_mov_b32_e32 v59, v48
	v_mov_b32_e32 v52, v48
	v_mov_b32_e32 v53, v48
	v_mov_b32_e32 v54, v48
	v_mov_b32_e32 v55, v48
	v_mov_b32_e32 v33, v32
	v_mov_b32_e32 v34, v32
	v_mov_b32_e32 v35, v32
	v_mov_b32_e32 v36, v32
	v_mov_b32_e32 v37, v32
	v_mov_b32_e32 v38, v32
	v_mov_b32_e32 v39, v32
	v_mov_b32_e32 v40, v32
	v_mov_b32_e32 v41, v32
	v_mov_b32_e32 v42, v32
	v_mov_b32_e32 v43, v32
	v_mov_b32_e32 v44, v32
	v_mov_b32_e32 v45, v32
	v_mov_b32_e32 v46, v32
	v_mov_b32_e32 v47, v32
	v_mov_b32_e32 v16, v48
	v_mov_b32_e32 v17, v48
	v_mov_b32_e32 v18, v48
	v_mov_b32_e32 v19, v48
	v_mov_b32_e32 v20, v48
	v_mov_b32_e32 v21, v48
	v_mov_b32_e32 v22, v48
	v_mov_b32_e32 v23, v48
	v_mov_b32_e32 v24, v48
	v_mov_b32_e32 v25, v48
	v_mov_b32_e32 v26, v48
	v_mov_b32_e32 v27, v48
	v_mov_b32_e32 v28, v48
	v_mov_b32_e32 v29, v48
	v_mov_b32_e32 v30, v48
	v_mov_b32_e32 v31, v48
	v_mov_b32_e32 v0, v48
	v_mov_b32_e32 v1, v48
	v_mov_b32_e32 v2, v48
	v_mov_b32_e32 v3, v48
	v_mov_b32_e32 v4, v48
	v_mov_b32_e32 v5, v48
	v_mov_b32_e32 v6, v48
	v_mov_b32_e32 v7, v48
	v_mov_b32_e32 v8, v48
	v_mov_b32_e32 v9, v48
	v_mov_b32_e32 v10, v48
	v_mov_b32_e32 v11, v48
	v_mov_b32_e32 v12, v48
	v_mov_b32_e32 v13, v48
	v_mov_b32_e32 v14, v48
	v_mov_b32_e32 v15, v48
	s_cmp_eq_u32 s44, 0
	s_cbranch_scc1 .Lswa_p
	s_setprio 1
.Lswa_p:
.LBB0_1324:
	s_mov_b32 s48, s0
	s_add_i32 s0, s29, -2
	s_and_b32 s34, s0, 1
	s_add_i32 s0, s30, s29
	s_waitcnt vmcnt(0) lgkmcnt(0)
	s_barrier
	s_add_i32 s0, s0, -1
	s_cmp_ge_u32 s0, s26
	s_cbranch_scc1 .LBB0_1326
	s_xor_b32 s0, s34, 1
	s_mulk_i32 s0, 0x3000
	s_add_i32 s0, s0, s27
	s_mov_b32 s1, m0
	s_mov_b32 m0, s0
	s_nop 0
	global_load_lds_dwordx4 v[138:139], off
	s_mov_b32 m0, s1
	s_lshl_b32 s0, s48, 13
	s_addk_i32 s0, 0x2000
	s_cmp_lg_u32 s48, 2
	s_cselect_b32 s0, s0, 0
	s_add_i32 s0, s0, s28
	s_mov_b32 s1, m0
	s_mov_b32 m0, s0
	s_nop 0
	global_load_lds_dwordx4 v[140:141], off
	s_mov_b32 m0, s1

; template <int MODE> __device__ __forceinline__ void attn_unit(const Unit& a, char* shm) {
;     ...
;     if (pend) ATT_PV(pw, svp);
.LBB0_1340:
	s_setprio 0
	s_lshl_b32 s0, s48, 13
	s_and_b64 vcc, exec, s[46:47]
	s_cbranch_vccz .LBB0_1342
	v_add_u32_e32 v36, s0, v164
	ds_read_b64_tr_b16 v[32:33], v36 offset:24576
	ds_read_b64_tr_b16 v[34:35], v36 offset:25088
	s_waitcnt lgkmcnt(0)
	v_mfma_f32_32x32x16_bf16 v[16:31], v[48:51], v[32:35], v[16:31]
	ds_read_b64_tr_b16 v[32:33], v36 offset:25600
	ds_read_b64_tr_b16 v[34:35], v36 offset:26112
	s_waitcnt lgkmcnt(0)
	v_mfma_f32_32x32x16_bf16 v[16:31], v[60:63], v[32:35], v[16:31]
	ds_read_b64_tr_b16 v[32:33], v36 offset:26624
	ds_read_b64_tr_b16 v[34:35], v36 offset:27136
	s_waitcnt lgkmcnt(0)
	v_mfma_f32_32x32x16_bf16 v[16:31], v[56:59], v[32:35], v[16:31]
	ds_read_b64_tr_b16 v[32:33], v36 offset:27648
	ds_read_b64_tr_b16 v[34:35], v36 offset:28160
	s_waitcnt lgkmcnt(0)
	v_mfma_f32_32x32x16_bf16 v[16:31], v[52:55], v[32:35], v[16:31]
	ds_read_b64_tr_b16 v[32:33], v36 offset:28672
	ds_read_b64_tr_b16 v[34:35], v36 offset:29184
	s_waitcnt lgkmcnt(0)
	v_mfma_f32_32x32x16_bf16 v[0:15], v[48:51], v[32:35], v[0:15]
	ds_read_b64_tr_b16 v[32:33], v36 offset:29696
	ds_read_b64_tr_b16 v[34:35], v36 offset:30208
	s_waitcnt lgkmcnt(0)
	v_mfma_f32_32x32x16_bf16 v[0:15], v[60:63], v[32:35], v[0:15]
	ds_read_b64_tr_b16 v[32:33], v36 offset:30720
	ds_read_b64_tr_b16 v[34:35], v36 offset:31232
	s_waitcnt lgkmcnt(0)
	v_mfma_f32_32x32x16_bf16 v[0:15], v[56:59], v[32:35], v[0:15]
	ds_read_b64_tr_b16 v[32:33], v36 offset:31744
	ds_read_b64_tr_b16 v[34:35], v36 offset:32256
	s_waitcnt lgkmcnt(0)
	v_mfma_f32_32x32x16_bf16 v[0:15], v[52:55], v[32:35], v[0:15]
